# P3: keep half of the gate_a tile loaded in mid() in spare VGPRs and reuse it in the epilogue (32 MiB less HBM re-read)
# baseline (speedup 1.0000x reference)
.LBB0_633:
	s_cmp_lg_u32 s95, 8
	s_cbranch_scc1 .LBB0_612
	v_mov_b32_e32 v128, v145
	s_nop 0
	v_add_u32_e32 v157, s70, v128
	v_add_u32_e32 v128, s19, v157
	v_mad_i64_i32 v[128:129], s[56:57], v128, s60, v[152:153]
	v_lshlrev_b64 v[132:133], 1, v[128:129]
	v_lshl_add_u64 v[128:129], s[12:13], 0, v[132:133]
	v_lshl_add_u64 v[134:135], s[14:15], 0, v[132:133]
	v_or_b32_e32 v132, 0x100, v132
	global_load_dwordx4 v[128:131], v[128:129], off
	s_nop 0
	global_load_dwordx4 v[158:161], v[134:135], off
	v_lshl_add_u64 v[134:135], s[12:13], 0, v[132:133]
	global_load_dwordx4 v[162:165], v[134:135], off
	v_lshl_add_u64 v[132:133], s[14:15], 0, v[132:133]
	global_load_dwordx4 v[166:169], v[132:133], off
	v_add_u32_e32 v132, s88, v157
	v_mad_i64_i32 v[132:133], s[56:57], v132, s60, v[152:153]
	v_lshlrev_b64 v[132:133], 1, v[132:133]
	v_lshl_add_u64 v[134:135], s[12:13], 0, v[132:133]
	v_lshl_add_u64 v[174:175], s[14:15], 0, v[132:133]
	v_or_b32_e32 v132, 0x100, v132
	global_load_dwordx4 v[170:173], v[134:135], off
	s_nop 0
	global_load_dwordx4 v[174:177], v[174:175], off
	v_lshl_add_u64 v[134:135], s[12:13], 0, v[132:133]
	v_lshl_add_u64 v[132:133], s[14:15], 0, v[132:133]
	global_load_dwordx4 v[178:181], v[134:135], off
	s_nop 0
	global_load_dwordx4 v[132:135], v[132:133], off
	s_waitcnt vmcnt(0)
	v_mov_b64_e32 v[216:217], v[128:129]
	v_mov_b64_e32 v[218:219], v[130:131]
	v_mov_b64_e32 v[220:221], v[162:163]
	v_mov_b64_e32 v[222:223], v[164:165]
	v_mov_b64_e32 v[224:225], v[170:171]
	v_mov_b64_e32 v[226:227], v[172:173]
	v_mov_b64_e32 v[228:229], v[178:179]
	v_mov_b64_e32 v[230:231], v[180:181]
	v_lshlrev_b32_e32 v182, 16, v128
	v_and_b32_e32 v183, 0xffff0000, v128
	v_lshlrev_b32_e32 v186, 16, v129
	v_and_b32_e32 v187, 0xffff0000, v129
	v_lshlrev_b32_e32 v184, 16, v130
	v_and_b32_e32 v185, 0xffff0000, v130
	v_lshlrev_b32_e32 v188, 16, v131
	v_and_b32_e32 v189, 0xffff0000, v131
	v_rcp_f32_e32 v182, v182
	v_rcp_f32_e32 v184, v184
	v_rcp_f32_e32 v183, v183
	v_rcp_f32_e32 v185, v185
	v_rcp_f32_e32 v186, v186
	v_rcp_f32_e32 v188, v188
	v_rcp_f32_e32 v187, v187
	v_rcp_f32_e32 v189, v189
	v_lshlrev_b32_e32 v190, 16, v162
	v_and_b32_e32 v191, 0xffff0000, v162
	v_lshlrev_b32_e32 v194, 16, v163
	v_and_b32_e32 v195, 0xffff0000, v163
	v_lshlrev_b32_e32 v192, 16, v164
	v_and_b32_e32 v193, 0xffff0000, v164
	v_lshlrev_b32_e32 v196, 16, v165
	v_and_b32_e32 v197, 0xffff0000, v165
	v_rcp_f32_e32 v190, v190
	v_rcp_f32_e32 v192, v192
	v_rcp_f32_e32 v191, v191
	v_rcp_f32_e32 v193, v193
	v_rcp_f32_e32 v194, v194
	v_rcp_f32_e32 v196, v196
	v_rcp_f32_e32 v195, v195
	v_rcp_f32_e32 v197, v197
	v_lshlrev_b32_e32 v128, 16, v158
	v_and_b32_e32 v129, 0xffff0000, v158
	v_lshlrev_b32_e32 v130, 16, v160
	v_and_b32_e32 v131, 0xffff0000, v160
	v_lshlrev_b32_e32 v158, 16, v159
	v_and_b32_e32 v159, 0xffff0000, v159
	v_lshlrev_b32_e32 v160, 16, v161
	v_and_b32_e32 v161, 0xffff0000, v161
	v_lshlrev_b32_e32 v162, 16, v166
	v_and_b32_e32 v163, 0xffff0000, v166
	v_lshlrev_b32_e32 v164, 16, v168
	v_and_b32_e32 v165, 0xffff0000, v168
	v_lshlrev_b32_e32 v166, 16, v167
	v_and_b32_e32 v167, 0xffff0000, v167
	v_lshlrev_b32_e32 v168, 16, v169
	v_and_b32_e32 v169, 0xffff0000, v169
	v_pk_mul_f32 v[128:129], v[182:183], v[128:129]
	v_pk_mul_f32 v[130:131], v[184:185], v[130:131]
	v_pk_mul_f32 v[158:159], v[186:187], v[158:159]
	v_pk_mul_f32 v[160:161], v[188:189], v[160:161]
	v_pk_mul_f32 v[124:125], v[124:125], v[128:129]
	v_pk_mul_f32 v[120:121], v[120:121], v[130:131]
	v_pk_mul_f32 v[126:127], v[126:127], v[158:159]
	v_pk_mul_f32 v[122:123], v[122:123], v[160:161]
	v_pk_mul_f32 v[128:129], v[190:191], v[162:163]
	v_pk_mul_f32 v[130:131], v[192:193], v[164:165]
	v_pk_mul_f32 v[158:159], v[194:195], v[166:167]
	v_pk_mul_f32 v[160:161], v[196:197], v[168:169]
	v_pk_mul_f32 v[116:117], v[116:117], v[128:129]
	v_pk_mul_f32 v[108:109], v[108:109], v[130:131]
	v_pk_mul_f32 v[118:119], v[118:119], v[158:159]
	v_pk_mul_f32 v[110:111], v[110:111], v[160:161]
	v_add_u32_e32 v128, s89, v157
	v_mad_i64_i32 v[128:129], s[56:57], v128, s60, v[152:153]
	v_lshlrev_b64 v[128:129], 1, v[128:129]
	v_lshlrev_b32_e32 v162, 16, v170
	v_and_b32_e32 v163, 0xffff0000, v170
	v_lshl_add_u64 v[130:131], s[12:13], 0, v[128:129]
	global_load_dwordx4 v[158:161], v[130:131], off
	v_rcp_f32_e32 v130, v162
	v_rcp_f32_e32 v131, v163
	v_lshlrev_b32_e32 v164, 16, v172
	v_and_b32_e32 v167, 0xffff0000, v172
	v_rcp_f32_e32 v166, v164
	v_lshlrev_b32_e32 v162, 16, v174
	v_and_b32_e32 v163, 0xffff0000, v174
	v_rcp_f32_e32 v167, v167
	v_pk_mul_f32 v[130:131], v[130:131], v[162:163]
	v_lshl_add_u64 v[162:163], s[14:15], 0, v[128:129]
	global_load_dwordx4 v[162:165], v[162:163], off
	v_pk_mul_f32 v[112:113], v[112:113], v[130:131]
	v_lshlrev_b32_e32 v130, 16, v176
	v_and_b32_e32 v131, 0xffff0000, v176
	v_lshlrev_b32_e32 v168, 16, v171
	v_and_b32_e32 v169, 0xffff0000, v171
	v_pk_mul_f32 v[130:131], v[166:167], v[130:131]
	v_lshlrev_b32_e32 v170, 16, v173
	v_pk_mul_f32 v[104:105], v[104:105], v[130:131]
	v_rcp_f32_e32 v130, v168
	v_rcp_f32_e32 v131, v169
	v_and_b32_e32 v171, 0xffff0000, v173
	v_rcp_f32_e32 v166, v170
	v_rcp_f32_e32 v167, v171
	v_lshlrev_b32_e32 v168, 16, v175
	v_and_b32_e32 v169, 0xffff0000, v175
	v_pk_mul_f32 v[130:131], v[130:131], v[168:169]
	v_or_b32_e32 v128, 0x100, v128
	v_pk_mul_f32 v[114:115], v[114:115], v[130:131]
	v_lshlrev_b32_e32 v130, 16, v177
	v_and_b32_e32 v131, 0xffff0000, v177
	v_pk_mul_f32 v[130:131], v[166:167], v[130:131]
	v_lshlrev_b32_e32 v190, 16, v179
	v_pk_mul_f32 v[106:107], v[106:107], v[130:131]
	v_lshl_add_u64 v[130:131], s[12:13], 0, v[128:129]
	global_load_dwordx4 v[166:169], v[130:131], off
	v_lshl_add_u64 v[128:129], s[14:15], 0, v[128:129]
	global_load_dwordx4 v[170:173], v[128:129], off
	v_lshlrev_b32_e32 v130, 16, v178
	v_and_b32_e32 v131, 0xffff0000, v178
	v_rcp_f32_e32 v130, v130
	v_rcp_f32_e32 v131, v131
	v_lshlrev_b32_e32 v128, 16, v132
	v_and_b32_e32 v129, 0xffff0000, v132
	v_and_b32_e32 v191, 0xffff0000, v179
	v_pk_mul_f32 v[128:129], v[130:131], v[128:129]
	v_lshlrev_b32_e32 v174, 16, v180
	v_pk_mul_f32 v[100:101], v[100:101], v[128:129]
	v_add_u32_e32 v128, s90, v157
	v_mad_i64_i32 v[128:129], s[56:57], v128, s60, v[152:153]
	v_lshlrev_b64 v[128:129], 1, v[128:129]
	v_and_b32_e32 v175, 0xffff0000, v180
	v_lshl_add_u64 v[130:131], s[12:13], 0, v[128:129]
	v_lshl_add_u64 v[178:179], s[14:15], 0, v[128:129]
	v_or_b32_e32 v128, 0x100, v128
	v_lshlrev_b32_e32 v192, 16, v181
	v_and_b32_e32 v193, 0xffff0000, v181
	v_rcp_f32_e32 v186, v174
	v_rcp_f32_e32 v187, v175
	global_load_dwordx4 v[174:177], v[130:131], off
	s_nop 0
	global_load_dwordx4 v[178:181], v[178:179], off
	v_lshl_add_u64 v[130:131], s[12:13], 0, v[128:129]
	v_lshl_add_u64 v[128:129], s[14:15], 0, v[128:129]
	global_load_dwordx4 v[182:185], v[130:131], off
	s_nop 0
	global_load_dwordx4 v[128:131], v[128:129], off
	v_lshlrev_b32_e32 v188, 16, v134
	v_and_b32_e32 v189, 0xffff0000, v134
	v_pk_mul_f32 v[186:187], v[186:187], v[188:189]
	v_rcp_f32_e32 v132, v192
	v_lshlrev_b32_e32 v188, 16, v133
	v_and_b32_e32 v189, 0xffff0000, v133
	v_rcp_f32_e32 v133, v193
	v_lshlrev_b32_e32 v134, 16, v135
	v_and_b32_e32 v135, 0xffff0000, v135
	v_pk_mul_f32 v[92:93], v[92:93], v[186:187]
	v_rcp_f32_e32 v186, v190
	v_rcp_f32_e32 v187, v191
	v_pk_mul_f32 v[132:133], v[132:133], v[134:135]
	s_waitcnt vmcnt(0)
	v_mov_b64_e32 v[232:233], v[158:159]
	v_mov_b64_e32 v[234:235], v[160:161]
	v_mov_b64_e32 v[236:237], v[166:167]
	v_mov_b64_e32 v[238:239], v[168:169]
	v_mov_b64_e32 v[240:241], v[174:175]
	v_mov_b64_e32 v[242:243], v[176:177]
	v_mov_b64_e32 v[244:245], v[182:183]
	v_mov_b64_e32 v[246:247], v[184:185]
	v_lshlrev_b32_e32 v134, 16, v160
	v_pk_mul_f32 v[94:95], v[94:95], v[132:133]
	v_lshlrev_b32_e32 v132, 16, v158
	v_and_b32_e32 v133, 0xffff0000, v158
	v_rcp_f32_e32 v132, v132
	v_rcp_f32_e32 v133, v133
	v_and_b32_e32 v135, 0xffff0000, v160
	v_pk_mul_f32 v[186:187], v[186:187], v[188:189]
	v_rcp_f32_e32 v134, v134
	v_rcp_f32_e32 v135, v135
	v_pk_mul_f32 v[102:103], v[102:103], v[186:187]
	v_lshlrev_b32_e32 v186, 16, v159
	v_and_b32_e32 v187, 0xffff0000, v159
	v_lshlrev_b32_e32 v158, 16, v162
	v_and_b32_e32 v159, 0xffff0000, v162
	v_pk_mul_f32 v[132:133], v[132:133], v[158:159]
	v_lshlrev_b32_e32 v160, 16, v161
	v_pk_mul_f32 v[96:97], v[96:97], v[132:133]
	v_lshlrev_b32_e32 v132, 16, v164
	v_and_b32_e32 v133, 0xffff0000, v164
	v_pk_mul_f32 v[132:133], v[134:135], v[132:133]
	v_and_b32_e32 v161, 0xffff0000, v161
	v_pk_mul_f32 v[88:89], v[88:89], v[132:133]
	v_rcp_f32_e32 v132, v186
	v_rcp_f32_e32 v133, v187
	v_rcp_f32_e32 v134, v160
	v_rcp_f32_e32 v135, v161
	v_lshlrev_b32_e32 v158, 16, v163
	v_and_b32_e32 v159, 0xffff0000, v163
	v_pk_mul_f32 v[132:133], v[132:133], v[158:159]
	v_lshlrev_b32_e32 v160, 16, v167
	v_pk_mul_f32 v[98:99], v[98:99], v[132:133]
	v_lshlrev_b32_e32 v132, 16, v165
	v_and_b32_e32 v133, 0xffff0000, v165
	v_pk_mul_f32 v[132:133], v[134:135], v[132:133]
	v_lshlrev_b32_e32 v134, 16, v168
	v_pk_mul_f32 v[90:91], v[90:91], v[132:133]
	v_lshlrev_b32_e32 v132, 16, v166
	v_and_b32_e32 v133, 0xffff0000, v166
	v_rcp_f32_e32 v132, v132
	v_rcp_f32_e32 v133, v133
	v_and_b32_e32 v135, 0xffff0000, v168
	v_rcp_f32_e32 v134, v134
	v_rcp_f32_e32 v135, v135
	v_lshlrev_b32_e32 v158, 16, v170
	v_and_b32_e32 v159, 0xffff0000, v170
	v_pk_mul_f32 v[132:133], v[132:133], v[158:159]
	v_and_b32_e32 v161, 0xffff0000, v167
	v_pk_mul_f32 v[84:85], v[84:85], v[132:133]
	v_lshlrev_b32_e32 v132, 16, v172
	v_and_b32_e32 v133, 0xffff0000, v172
	v_pk_mul_f32 v[132:133], v[134:135], v[132:133]
	v_lshlrev_b32_e32 v162, 16, v169
	v_pk_mul_f32 v[76:77], v[76:77], v[132:133]
	v_rcp_f32_e32 v132, v160
	v_rcp_f32_e32 v133, v161
	v_and_b32_e32 v163, 0xffff0000, v169
	v_rcp_f32_e32 v134, v162
	v_rcp_f32_e32 v135, v163
	v_lshlrev_b32_e32 v158, 16, v171
	v_and_b32_e32 v159, 0xffff0000, v171
	v_pk_mul_f32 v[132:133], v[132:133], v[158:159]
	s_nop 0
	v_pk_mul_f32 v[86:87], v[86:87], v[132:133]
	v_lshlrev_b32_e32 v132, 16, v173
	v_and_b32_e32 v133, 0xffff0000, v173
	v_pk_mul_f32 v[132:133], v[134:135], v[132:133]
	s_nop 0
	v_pk_mul_f32 v[78:79], v[78:79], v[132:133]
	v_add_u32_e32 v132, s91, v157
	v_mad_i64_i32 v[132:133], s[56:57], v132, s60, v[152:153]
	v_lshlrev_b64 v[132:133], 1, v[132:133]
	v_lshlrev_b32_e32 v162, 16, v174
	v_and_b32_e32 v163, 0xffff0000, v174
	v_lshl_add_u64 v[134:135], s[12:13], 0, v[132:133]
	global_load_dwordx4 v[158:161], v[134:135], off
	v_rcp_f32_e32 v134, v162
	v_rcp_f32_e32 v135, v163
	v_lshlrev_b32_e32 v164, 16, v176
	v_and_b32_e32 v167, 0xffff0000, v176
	v_rcp_f32_e32 v166, v164
	v_lshlrev_b32_e32 v162, 16, v178
	v_and_b32_e32 v163, 0xffff0000, v178
	v_rcp_f32_e32 v167, v167
	v_pk_mul_f32 v[134:135], v[134:135], v[162:163]
	v_lshl_add_u64 v[162:163], s[14:15], 0, v[132:133]
	global_load_dwordx4 v[162:165], v[162:163], off
	v_pk_mul_f32 v[80:81], v[80:81], v[134:135]
	v_lshlrev_b32_e32 v134, 16, v180
	v_and_b32_e32 v135, 0xffff0000, v180
	v_lshlrev_b32_e32 v168, 16, v175
	v_and_b32_e32 v169, 0xffff0000, v175
	v_pk_mul_f32 v[134:135], v[166:167], v[134:135]
	v_lshlrev_b32_e32 v170, 16, v177
	v_pk_mul_f32 v[72:73], v[72:73], v[134:135]
	v_rcp_f32_e32 v134, v168
	v_rcp_f32_e32 v135, v169
	v_and_b32_e32 v171, 0xffff0000, v177
	v_rcp_f32_e32 v166, v170
	v_rcp_f32_e32 v167, v171
	v_lshlrev_b32_e32 v168, 16, v179
	v_and_b32_e32 v169, 0xffff0000, v179
	v_pk_mul_f32 v[134:135], v[134:135], v[168:169]
	v_or_b32_e32 v132, 0x100, v132
	v_pk_mul_f32 v[82:83], v[82:83], v[134:135]
	v_lshlrev_b32_e32 v134, 16, v181
	v_and_b32_e32 v135, 0xffff0000, v181
	v_pk_mul_f32 v[134:135], v[166:167], v[134:135]
	v_lshlrev_b32_e32 v174, 16, v184
	v_pk_mul_f32 v[74:75], v[74:75], v[134:135]
	v_lshl_add_u64 v[134:135], s[12:13], 0, v[132:133]
	global_load_dwordx4 v[166:169], v[134:135], off
	v_lshl_add_u64 v[132:133], s[14:15], 0, v[132:133]
	global_load_dwordx4 v[170:173], v[132:133], off
	v_lshlrev_b32_e32 v134, 16, v182
	v_and_b32_e32 v135, 0xffff0000, v182
	v_rcp_f32_e32 v134, v134
	v_rcp_f32_e32 v135, v135
	v_lshlrev_b32_e32 v132, 16, v128
	v_and_b32_e32 v133, 0xffff0000, v128
	v_add_u32_e32 v128, s92, v157
	v_pk_mul_f32 v[132:133], v[134:135], v[132:133]
	v_and_b32_e32 v175, 0xffff0000, v184
	v_pk_mul_f32 v[68:69], v[68:69], v[132:133]
	v_mad_i64_i32 v[132:133], s[56:57], v128, s60, v[152:153]
	v_lshlrev_b64 v[132:133], 1, v[132:133]
	v_lshl_add_u64 v[134:135], s[12:13], 0, v[132:133]
	v_lshl_add_u64 v[178:179], s[14:15], 0, v[132:133]
	v_or_b32_e32 v132, 0x100, v132
	v_rcp_f32_e32 v186, v174
	v_rcp_f32_e32 v187, v175
	global_load_dwordx4 v[174:177], v[134:135], off
	s_nop 0
	global_load_dwordx4 v[178:181], v[178:179], off
	v_lshl_add_u64 v[134:135], s[12:13], 0, v[132:133]
	v_lshl_add_u64 v[132:133], s[14:15], 0, v[132:133]
	v_lshlrev_b32_e32 v190, 16, v183
	v_and_b32_e32 v191, 0xffff0000, v183
	v_lshlrev_b32_e32 v192, 16, v185
	v_and_b32_e32 v193, 0xffff0000, v185
	global_load_dwordx4 v[182:185], v[134:135], off
	s_nop 0
	global_load_dwordx4 v[132:135], v[132:133], off
	v_lshlrev_b32_e32 v188, 16, v130
	v_and_b32_e32 v189, 0xffff0000, v130
	v_pk_mul_f32 v[186:187], v[186:187], v[188:189]
	v_rcp_f32_e32 v128, v192
	v_lshlrev_b32_e32 v188, 16, v129
	v_and_b32_e32 v189, 0xffff0000, v129
	v_rcp_f32_e32 v129, v193
	v_lshlrev_b32_e32 v130, 16, v131
	v_and_b32_e32 v131, 0xffff0000, v131
	v_pk_mul_f32 v[64:65], v[64:65], v[186:187]
	v_rcp_f32_e32 v186, v190
	v_rcp_f32_e32 v187, v191
	v_pk_mul_f32 v[128:129], v[128:129], v[130:131]
	s_waitcnt vmcnt(0)
	v_lshlrev_b32_e32 v130, 16, v160
	v_pk_mul_f32 v[66:67], v[66:67], v[128:129]
	v_lshlrev_b32_e32 v128, 16, v158
	v_and_b32_e32 v129, 0xffff0000, v158
	v_rcp_f32_e32 v128, v128
	v_rcp_f32_e32 v129, v129
	v_and_b32_e32 v131, 0xffff0000, v160
	v_pk_mul_f32 v[186:187], v[186:187], v[188:189]
	v_rcp_f32_e32 v130, v130
	v_rcp_f32_e32 v131, v131
	v_pk_mul_f32 v[70:71], v[70:71], v[186:187]
	v_lshlrev_b32_e32 v186, 16, v159
	v_and_b32_e32 v187, 0xffff0000, v159
	v_lshlrev_b32_e32 v158, 16, v162
	v_and_b32_e32 v159, 0xffff0000, v162
	v_pk_mul_f32 v[128:129], v[128:129], v[158:159]
	v_lshlrev_b32_e32 v160, 16, v161
	v_pk_mul_f32 v[60:61], v[60:61], v[128:129]
	v_lshlrev_b32_e32 v128, 16, v164
	v_and_b32_e32 v129, 0xffff0000, v164
	v_pk_mul_f32 v[128:129], v[130:131], v[128:129]
	v_and_b32_e32 v161, 0xffff0000, v161
	v_pk_mul_f32 v[56:57], v[56:57], v[128:129]
	v_rcp_f32_e32 v128, v186
	v_rcp_f32_e32 v129, v187
	v_rcp_f32_e32 v130, v160
	v_rcp_f32_e32 v131, v161
	v_lshlrev_b32_e32 v158, 16, v163
	v_and_b32_e32 v159, 0xffff0000, v163
	v_pk_mul_f32 v[128:129], v[128:129], v[158:159]
	v_lshlrev_b32_e32 v160, 16, v167
	v_pk_mul_f32 v[62:63], v[62:63], v[128:129]
	v_lshlrev_b32_e32 v128, 16, v165
	v_and_b32_e32 v129, 0xffff0000, v165
	v_pk_mul_f32 v[128:129], v[130:131], v[128:129]
	v_lshlrev_b32_e32 v130, 16, v168
	v_pk_mul_f32 v[58:59], v[58:59], v[128:129]
	v_lshlrev_b32_e32 v128, 16, v166
	v_and_b32_e32 v129, 0xffff0000, v166
	v_rcp_f32_e32 v128, v128
	v_rcp_f32_e32 v129, v129
	v_and_b32_e32 v131, 0xffff0000, v168
	v_rcp_f32_e32 v130, v130
	v_rcp_f32_e32 v131, v131
	v_lshlrev_b32_e32 v158, 16, v170
	v_and_b32_e32 v159, 0xffff0000, v170
	v_pk_mul_f32 v[128:129], v[128:129], v[158:159]
	v_and_b32_e32 v161, 0xffff0000, v167
	v_pk_mul_f32 v[52:53], v[52:53], v[128:129]
	v_lshlrev_b32_e32 v128, 16, v172
	v_and_b32_e32 v129, 0xffff0000, v172
	v_pk_mul_f32 v[128:129], v[130:131], v[128:129]
	v_lshlrev_b32_e32 v162, 16, v169
	v_pk_mul_f32 v[44:45], v[44:45], v[128:129]
	v_rcp_f32_e32 v128, v160
	v_rcp_f32_e32 v129, v161
	v_and_b32_e32 v163, 0xffff0000, v169
	v_rcp_f32_e32 v130, v162
	v_rcp_f32_e32 v131, v163
	v_lshlrev_b32_e32 v158, 16, v171
	v_and_b32_e32 v159, 0xffff0000, v171
	v_pk_mul_f32 v[128:129], v[128:129], v[158:159]
	s_nop 0
	v_pk_mul_f32 v[54:55], v[54:55], v[128:129]
	v_lshlrev_b32_e32 v128, 16, v173
	v_and_b32_e32 v129, 0xffff0000, v173
	v_pk_mul_f32 v[128:129], v[130:131], v[128:129]
	s_nop 0
	v_pk_mul_f32 v[46:47], v[46:47], v[128:129]
	v_add_u32_e32 v128, s93, v157
	v_mad_i64_i32 v[128:129], s[56:57], v128, s60, v[152:153]
	v_lshlrev_b32_e32 v158, 16, v174
	v_and_b32_e32 v159, 0xffff0000, v174
	v_lshlrev_b64 v[166:167], 1, v[128:129]
	v_lshl_add_u64 v[128:129], s[12:13], 0, v[166:167]
	v_rcp_f32_e32 v158, v158
	v_rcp_f32_e32 v159, v159
	global_load_dwordx4 v[128:131], v[128:129], off
	v_lshlrev_b32_e32 v160, 16, v176
	v_and_b32_e32 v163, 0xffff0000, v176
	v_rcp_f32_e32 v162, v160
	v_lshlrev_b32_e32 v160, 16, v178
	v_and_b32_e32 v161, 0xffff0000, v178
	v_rcp_f32_e32 v163, v163
	v_pk_mul_f32 v[164:165], v[158:159], v[160:161]
	v_lshl_add_u64 v[158:159], s[14:15], 0, v[166:167]
	global_load_dwordx4 v[158:161], v[158:159], off
	v_pk_mul_f32 v[48:49], v[48:49], v[164:165]
	v_lshlrev_b32_e32 v164, 16, v180
	v_and_b32_e32 v165, 0xffff0000, v180
	v_lshlrev_b32_e32 v168, 16, v175
	v_and_b32_e32 v169, 0xffff0000, v175
	v_pk_mul_f32 v[162:163], v[162:163], v[164:165]
	v_lshlrev_b32_e32 v170, 16, v177
	v_pk_mul_f32 v[40:41], v[40:41], v[162:163]
	v_rcp_f32_e32 v162, v168
	v_rcp_f32_e32 v163, v169
	v_and_b32_e32 v171, 0xffff0000, v177
	v_rcp_f32_e32 v164, v170
	v_rcp_f32_e32 v165, v171
	v_lshlrev_b32_e32 v168, 16, v179
	v_and_b32_e32 v169, 0xffff0000, v179
	v_pk_mul_f32 v[162:163], v[162:163], v[168:169]
	v_or_b32_e32 v166, 0x100, v166
	v_pk_mul_f32 v[50:51], v[50:51], v[162:163]
	v_lshlrev_b32_e32 v162, 16, v181
	v_and_b32_e32 v163, 0xffff0000, v181
	v_pk_mul_f32 v[162:163], v[164:165], v[162:163]
	v_lshlrev_b32_e32 v168, 16, v182
	v_pk_mul_f32 v[42:43], v[42:43], v[162:163]
	v_lshl_add_u64 v[162:163], s[12:13], 0, v[166:167]
	global_load_dwordx4 v[162:165], v[162:163], off
	v_lshl_add_u64 v[166:167], s[14:15], 0, v[166:167]
	v_rcp_f32_e32 v170, v168
	global_load_dwordx4 v[166:169], v[166:167], off
	v_and_b32_e32 v171, 0xffff0000, v182
	v_rcp_f32_e32 v171, v171
	v_lshlrev_b32_e32 v172, 16, v184
	v_rcp_f32_e32 v186, v172
	v_lshlrev_b32_e32 v172, 16, v132
	v_and_b32_e32 v173, 0xffff0000, v132
	v_pk_mul_f32 v[170:171], v[170:171], v[172:173]
	v_add_u32_e32 v132, s94, v157
	v_pk_mul_f32 v[36:37], v[36:37], v[170:171]
	v_mad_i64_i32 v[170:171], s[56:57], v132, s60, v[152:153]
	v_and_b32_e32 v174, 0xffff0000, v184
	v_lshlrev_b64 v[178:179], 1, v[170:171]
	v_rcp_f32_e32 v187, v174
	v_lshl_add_u64 v[170:171], s[12:13], 0, v[178:179]
	v_lshl_add_u64 v[174:175], s[14:15], 0, v[178:179]
	v_or_b32_e32 v178, 0x100, v178
	v_lshlrev_b32_e32 v190, 16, v183
	v_and_b32_e32 v191, 0xffff0000, v183
	v_lshl_add_u64 v[180:181], s[12:13], 0, v[178:179]
	v_lshl_add_u64 v[182:183], s[14:15], 0, v[178:179]
	v_lshlrev_b32_e32 v192, 16, v185
	v_and_b32_e32 v193, 0xffff0000, v185
	global_load_dwordx4 v[170:173], v[170:171], off
	s_nop 0
	global_load_dwordx4 v[174:177], v[174:175], off
	s_nop 0
	global_load_dwordx4 v[178:181], v[180:181], off
	s_nop 0
	global_load_dwordx4 v[182:185], v[182:183], off
	v_lshlrev_b32_e32 v188, 16, v134
	v_and_b32_e32 v189, 0xffff0000, v134
	v_pk_mul_f32 v[186:187], v[186:187], v[188:189]
	v_rcp_f32_e32 v132, v192
	v_lshlrev_b32_e32 v188, 16, v133
	v_and_b32_e32 v189, 0xffff0000, v133
	v_rcp_f32_e32 v133, v193
	v_pk_mul_f32 v[28:29], v[28:29], v[186:187]
	v_rcp_f32_e32 v186, v190
	v_rcp_f32_e32 v187, v191
	v_lshlrev_b32_e32 v134, 16, v135
	v_and_b32_e32 v135, 0xffff0000, v135
	v_pk_mul_f32 v[132:133], v[132:133], v[134:135]
	v_pk_mul_f32 v[186:187], v[186:187], v[188:189]
	v_pk_mul_f32 v[30:31], v[30:31], v[132:133]
	v_pk_mul_f32 v[38:39], v[38:39], v[186:187]
	s_waitcnt vmcnt(0)
	v_lshlrev_b32_e32 v132, 16, v128
	v_and_b32_e32 v133, 0xffff0000, v128
	v_lshlrev_b32_e32 v134, 16, v129
	v_and_b32_e32 v135, 0xffff0000, v129
	v_rcp_f32_e32 v128, v132
	v_rcp_f32_e32 v129, v133
	v_lshlrev_b32_e32 v157, 16, v130
	v_and_b32_e32 v186, 0xffff0000, v130
	v_lshlrev_b32_e32 v187, 16, v131
	v_and_b32_e32 v188, 0xffff0000, v131
	v_rcp_f32_e32 v130, v157
	v_rcp_f32_e32 v131, v186
	v_lshlrev_b32_e32 v132, 16, v158
	v_and_b32_e32 v133, 0xffff0000, v158
	v_pk_mul_f32 v[128:129], v[128:129], v[132:133]
	v_lshlrev_b32_e32 v132, 16, v159
	v_pk_mul_f32 v[32:33], v[32:33], v[128:129]
	v_lshlrev_b32_e32 v128, 16, v160
	v_and_b32_e32 v129, 0xffff0000, v160
	v_pk_mul_f32 v[128:129], v[130:131], v[128:129]
	v_rcp_f32_e32 v130, v187
	v_pk_mul_f32 v[24:25], v[24:25], v[128:129]
	v_rcp_f32_e32 v128, v134
	v_rcp_f32_e32 v129, v135
	v_rcp_f32_e32 v131, v188
	v_and_b32_e32 v133, 0xffff0000, v159
	v_pk_mul_f32 v[128:129], v[128:129], v[132:133]
	s_nop 0
	v_pk_mul_f32 v[34:35], v[34:35], v[128:129]
	v_lshlrev_b32_e32 v128, 16, v161
	v_and_b32_e32 v129, 0xffff0000, v161
	v_pk_mul_f32 v[128:129], v[130:131], v[128:129]
	v_lshlrev_b32_e32 v130, 16, v164
	v_pk_mul_f32 v[26:27], v[26:27], v[128:129]
	v_lshlrev_b32_e32 v128, 16, v162
	v_and_b32_e32 v129, 0xffff0000, v162
	v_rcp_f32_e32 v128, v128
	v_rcp_f32_e32 v129, v129
	v_and_b32_e32 v131, 0xffff0000, v164
	v_rcp_f32_e32 v130, v130
	v_rcp_f32_e32 v131, v131
	v_lshlrev_b32_e32 v132, 16, v166
	v_and_b32_e32 v133, 0xffff0000, v166
	v_pk_mul_f32 v[128:129], v[128:129], v[132:133]
	v_lshlrev_b32_e32 v134, 16, v163
	v_pk_mul_f32 v[20:21], v[20:21], v[128:129]
	v_lshlrev_b32_e32 v128, 16, v168
	v_and_b32_e32 v129, 0xffff0000, v168
	v_and_b32_e32 v135, 0xffff0000, v163
	v_pk_mul_f32 v[128:129], v[130:131], v[128:129]
	v_lshlrev_b32_e32 v157, 16, v165
	v_pk_mul_f32 v[12:13], v[12:13], v[128:129]
	v_rcp_f32_e32 v128, v134
	v_rcp_f32_e32 v129, v135
	v_and_b32_e32 v158, 0xffff0000, v165
	v_rcp_f32_e32 v130, v157
	v_rcp_f32_e32 v131, v158
	v_lshlrev_b32_e32 v132, 16, v167
	v_and_b32_e32 v133, 0xffff0000, v167
	v_pk_mul_f32 v[128:129], v[128:129], v[132:133]
	s_nop 0
	v_pk_mul_f32 v[22:23], v[22:23], v[128:129]
	v_lshlrev_b32_e32 v128, 16, v169
	v_and_b32_e32 v129, 0xffff0000, v169
	v_pk_mul_f32 v[128:129], v[130:131], v[128:129]
	s_nop 0
	v_pk_mul_f32 v[14:15], v[14:15], v[128:129]
	v_lshlrev_b32_e32 v128, 16, v170
	v_and_b32_e32 v129, 0xffff0000, v170
	v_rcp_f32_e32 v128, v128
	v_rcp_f32_e32 v129, v129
	v_lshlrev_b32_e32 v130, 16, v172
	v_and_b32_e32 v131, 0xffff0000, v172
	v_rcp_f32_e32 v130, v130
	v_rcp_f32_e32 v131, v131
	v_lshlrev_b32_e32 v132, 16, v174
	v_and_b32_e32 v133, 0xffff0000, v174
	v_pk_mul_f32 v[128:129], v[128:129], v[132:133]
	v_lshlrev_b32_e32 v134, 16, v171
	v_pk_mul_f32 v[16:17], v[16:17], v[128:129]
	v_lshlrev_b32_e32 v128, 16, v176
	v_and_b32_e32 v129, 0xffff0000, v176
	v_and_b32_e32 v135, 0xffff0000, v171
	v_pk_mul_f32 v[128:129], v[130:131], v[128:129]
	v_lshlrev_b32_e32 v157, 16, v173
	v_pk_mul_f32 v[8:9], v[8:9], v[128:129]
	v_rcp_f32_e32 v128, v134
	v_rcp_f32_e32 v129, v135
	v_and_b32_e32 v158, 0xffff0000, v173
	v_rcp_f32_e32 v130, v157
	v_rcp_f32_e32 v131, v158
	v_lshlrev_b32_e32 v132, 16, v175
	v_and_b32_e32 v133, 0xffff0000, v175
	v_pk_mul_f32 v[128:129], v[128:129], v[132:133]
	v_lshlrev_b32_e32 v132, 16, v182
	v_pk_mul_f32 v[18:19], v[18:19], v[128:129]
	v_lshlrev_b32_e32 v128, 16, v177
	v_and_b32_e32 v129, 0xffff0000, v177
	v_pk_mul_f32 v[128:129], v[130:131], v[128:129]
	v_lshlrev_b32_e32 v130, 16, v180
	v_pk_mul_f32 v[10:11], v[10:11], v[128:129]
	v_lshlrev_b32_e32 v128, 16, v178
	v_and_b32_e32 v129, 0xffff0000, v178
	v_rcp_f32_e32 v128, v128
	v_rcp_f32_e32 v129, v129
	v_and_b32_e32 v131, 0xffff0000, v180
	v_rcp_f32_e32 v130, v130
	v_rcp_f32_e32 v131, v131
	v_and_b32_e32 v133, 0xffff0000, v182
	v_pk_mul_f32 v[128:129], v[128:129], v[132:133]
	v_lshlrev_b32_e32 v134, 16, v179
	v_pk_mul_f32 v[4:5], v[4:5], v[128:129]
	v_lshlrev_b32_e32 v128, 16, v184
	v_and_b32_e32 v129, 0xffff0000, v184
	v_and_b32_e32 v135, 0xffff0000, v179
	v_pk_mul_f32 v[128:129], v[130:131], v[128:129]
	v_lshlrev_b32_e32 v157, 16, v181
	v_pk_mul_f32 v[0:1], v[0:1], v[128:129]
	v_rcp_f32_e32 v128, v134
	v_rcp_f32_e32 v129, v135
	v_and_b32_e32 v158, 0xffff0000, v181
	v_rcp_f32_e32 v130, v157
	v_rcp_f32_e32 v131, v158
	v_lshlrev_b32_e32 v132, 16, v183
	v_and_b32_e32 v133, 0xffff0000, v183
	v_pk_mul_f32 v[128:129], v[128:129], v[132:133]
	s_nop 0
	v_pk_mul_f32 v[6:7], v[6:7], v[128:129]
	v_lshlrev_b32_e32 v128, 16, v185
	v_and_b32_e32 v129, 0xffff0000, v185
	v_pk_mul_f32 v[128:129], v[130:131], v[128:129]
	s_nop 0
	v_pk_mul_f32 v[2:3], v[2:3], v[128:129]
	s_branch .LBB0_612

.LBB0_637:
	v_add_u32_e32 v134, s19, v154
	v_lshl_add_u64 v[132:133], s[30:31], 1, v[146:147]
	v_mad_i64_i32 v[128:129], s[4:5], v134, s81, v[132:133]
	v_or_b32_e32 v186, 16, v134
	v_mov_b64_e32 v[158:159], v[216:217]
	v_mov_b64_e32 v[160:161], v[218:219]
	v_mov_b64_e32 v[162:163], v[220:221]
	v_mov_b64_e32 v[164:165], v[222:223]
	v_mad_i64_i32 v[128:129], s[4:5], v186, s81, v[132:133]
	v_or_b32_e32 v188, 32, v134
	v_mov_b64_e32 v[166:167], v[224:225]
	v_mov_b64_e32 v[168:169], v[226:227]
	v_mov_b64_e32 v[170:171], v[228:229]
	v_mov_b64_e32 v[172:173], v[230:231]
	v_mad_i64_i32 v[128:129], s[4:5], v188, s81, v[132:133]
	v_or_b32_e32 v152, 48, v134
	v_mov_b64_e32 v[174:175], v[232:233]
	v_mov_b64_e32 v[176:177], v[234:235]
	v_mov_b64_e32 v[178:179], v[236:237]
	v_mov_b64_e32 v[180:181], v[238:239]
	v_mad_i64_i32 v[128:129], s[4:5], v152, s81, v[132:133]
	v_mov_b64_e32 v[182:183], v[240:241]
	v_mov_b64_e32 v[184:185], v[242:243]
	s_nop 0
	v_mov_b64_e32 v[128:129], v[244:245]
	v_mov_b64_e32 v[130:131], v[246:247]
	v_or_b32_e32 v190, s30, v144
	v_ashrrev_i32_e32 v135, 31, v134
	v_ashrrev_i32_e32 v187, 31, v186
	v_ashrrev_i32_e32 v189, 31, v188
	v_ashrrev_i32_e32 v153, 31, v152
	s_waitcnt vmcnt(0)
	v_lshlrev_b32_e32 v192, 16, v158
	v_and_b32_e32 v193, 0xffff0000, v158
	v_lshlrev_b32_e32 v158, 16, v159
	v_and_b32_e32 v159, 0xffff0000, v159
	v_pk_mul_f32 v[126:127], v[126:127], v[158:159]
	v_lshlrev_b32_e32 v158, 16, v160
	v_and_b32_e32 v159, 0xffff0000, v160
	v_pk_mul_f32 v[124:125], v[124:125], v[192:193]
	v_pk_mul_f32 v[120:121], v[120:121], v[158:159]
	v_lshlrev_b32_e32 v158, 16, v161
	v_and_b32_e32 v159, 0xffff0000, v161
	v_pk_mul_f32 v[158:159], v[122:123], v[158:159]
	v_cvt_pk_bf16_f32 v122, v124, v125
	v_cvt_pk_bf16_f32 v124, v120, v121
	v_lshlrev_b64 v[120:121], 11, v[134:135]
	v_ashrrev_i32_e32 v191, 31, v190
	v_cvt_pk_bf16_f32 v123, v126, v127
	v_lshl_add_u64 v[126:127], s[34:35], 0, v[120:121]
	v_lshlrev_b64 v[120:121], 1, v[190:191]
	v_cvt_pk_bf16_f32 v125, v158, v159
	v_lshl_add_u64 v[126:127], v[126:127], 0, v[120:121]
	global_store_dwordx4 v[126:127], v[122:125], off
	s_nop 1
	v_lshlrev_b32_e32 v122, 16, v162
	v_and_b32_e32 v123, 0xffff0000, v162
	v_pk_mul_f32 v[116:117], v[116:117], v[122:123]
	v_lshlrev_b32_e32 v122, 16, v163
	v_and_b32_e32 v123, 0xffff0000, v163
	v_pk_mul_f32 v[118:119], v[118:119], v[122:123]
	v_lshlrev_b32_e32 v122, 16, v164
	v_and_b32_e32 v123, 0xffff0000, v164
	v_pk_mul_f32 v[122:123], v[108:109], v[122:123]
	v_lshlrev_b32_e32 v108, 16, v165
	v_and_b32_e32 v109, 0xffff0000, v165
	v_pk_mul_f32 v[124:125], v[110:111], v[108:109]
	v_cvt_pk_bf16_f32 v108, v116, v117
	v_cvt_pk_bf16_f32 v109, v118, v119
	v_cvt_pk_bf16_f32 v110, v122, v123
	v_cvt_pk_bf16_f32 v111, v124, v125
	global_store_dwordx4 v[126:127], v[108:111], off offset:256
	s_nop 1
	v_lshlrev_b32_e32 v108, 16, v166
	v_and_b32_e32 v109, 0xffff0000, v166
	v_pk_mul_f32 v[108:109], v[112:113], v[108:109]
	v_lshlrev_b32_e32 v112, 16, v168
	v_and_b32_e32 v113, 0xffff0000, v168
	v_lshlrev_b32_e32 v110, 16, v167
	v_and_b32_e32 v111, 0xffff0000, v167
	v_pk_mul_f32 v[112:113], v[104:105], v[112:113]
	v_lshlrev_b32_e32 v104, 16, v169
	v_and_b32_e32 v105, 0xffff0000, v169
	v_pk_mul_f32 v[110:111], v[114:115], v[110:111]
	v_pk_mul_f32 v[114:115], v[106:107], v[104:105]
	v_cvt_pk_bf16_f32 v104, v108, v109
	v_lshlrev_b64 v[108:109], 11, v[186:187]
	v_lshl_add_u64 v[108:109], s[34:35], 0, v[108:109]
	v_cvt_pk_bf16_f32 v105, v110, v111
	v_cvt_pk_bf16_f32 v106, v112, v113
	v_cvt_pk_bf16_f32 v107, v114, v115
	v_lshl_add_u64 v[108:109], v[108:109], 0, v[120:121]
	global_store_dwordx4 v[108:109], v[104:107], off
	s_nop 1
	v_lshlrev_b32_e32 v104, 16, v170
	v_and_b32_e32 v105, 0xffff0000, v170
	v_pk_mul_f32 v[100:101], v[100:101], v[104:105]
	v_lshlrev_b32_e32 v104, 16, v171
	v_and_b32_e32 v105, 0xffff0000, v171
	v_pk_mul_f32 v[102:103], v[102:103], v[104:105]
	v_lshlrev_b32_e32 v104, 16, v172
	v_and_b32_e32 v105, 0xffff0000, v172
	v_pk_mul_f32 v[104:105], v[92:93], v[104:105]
	v_lshlrev_b32_e32 v92, 16, v173
	v_and_b32_e32 v93, 0xffff0000, v173
	v_pk_mul_f32 v[106:107], v[94:95], v[92:93]
	v_cvt_pk_bf16_f32 v92, v100, v101
	v_cvt_pk_bf16_f32 v93, v102, v103
	v_cvt_pk_bf16_f32 v94, v104, v105
	v_cvt_pk_bf16_f32 v95, v106, v107
	global_store_dwordx4 v[108:109], v[92:95], off offset:256
	s_nop 1
	v_lshlrev_b32_e32 v92, 16, v174
	v_and_b32_e32 v93, 0xffff0000, v174
	v_pk_mul_f32 v[92:93], v[96:97], v[92:93]
	v_lshlrev_b32_e32 v96, 16, v176
	v_and_b32_e32 v97, 0xffff0000, v176
	v_lshlrev_b32_e32 v94, 16, v175
	v_and_b32_e32 v95, 0xffff0000, v175
	v_pk_mul_f32 v[96:97], v[88:89], v[96:97]
	v_lshlrev_b32_e32 v88, 16, v177
	v_and_b32_e32 v89, 0xffff0000, v177
	v_pk_mul_f32 v[94:95], v[98:99], v[94:95]
	v_pk_mul_f32 v[98:99], v[90:91], v[88:89]
	v_cvt_pk_bf16_f32 v88, v92, v93
	v_lshlrev_b64 v[92:93], 11, v[188:189]
	v_lshl_add_u64 v[92:93], s[34:35], 0, v[92:93]
	v_cvt_pk_bf16_f32 v89, v94, v95
	v_cvt_pk_bf16_f32 v90, v96, v97
	v_cvt_pk_bf16_f32 v91, v98, v99
	v_lshl_add_u64 v[92:93], v[92:93], 0, v[120:121]
	global_store_dwordx4 v[92:93], v[88:91], off
	s_nop 1
	v_lshlrev_b32_e32 v88, 16, v178
	v_and_b32_e32 v89, 0xffff0000, v178
	v_pk_mul_f32 v[84:85], v[84:85], v[88:89]
	v_lshlrev_b32_e32 v88, 16, v179
	v_and_b32_e32 v89, 0xffff0000, v179
	v_pk_mul_f32 v[86:87], v[86:87], v[88:89]
	v_lshlrev_b32_e32 v88, 16, v180
	v_and_b32_e32 v89, 0xffff0000, v180
	v_pk_mul_f32 v[88:89], v[76:77], v[88:89]
	v_lshlrev_b32_e32 v76, 16, v181
	v_and_b32_e32 v77, 0xffff0000, v181
	v_pk_mul_f32 v[90:91], v[78:79], v[76:77]
	v_cvt_pk_bf16_f32 v76, v84, v85
	v_cvt_pk_bf16_f32 v77, v86, v87
	v_cvt_pk_bf16_f32 v78, v88, v89
	v_cvt_pk_bf16_f32 v79, v90, v91
	global_store_dwordx4 v[92:93], v[76:79], off offset:256
	s_nop 1
	v_lshlrev_b32_e32 v76, 16, v182
	v_and_b32_e32 v77, 0xffff0000, v182
	v_pk_mul_f32 v[76:77], v[80:81], v[76:77]
	v_lshlrev_b32_e32 v80, 16, v184
	v_and_b32_e32 v81, 0xffff0000, v184
	v_lshlrev_b32_e32 v78, 16, v183
	v_and_b32_e32 v79, 0xffff0000, v183
	v_pk_mul_f32 v[80:81], v[72:73], v[80:81]
	v_lshlrev_b32_e32 v72, 16, v185
	v_and_b32_e32 v73, 0xffff0000, v185
	v_pk_mul_f32 v[78:79], v[82:83], v[78:79]
	v_pk_mul_f32 v[82:83], v[74:75], v[72:73]
	v_cvt_pk_bf16_f32 v72, v76, v77
	v_lshlrev_b64 v[76:77], 11, v[152:153]
	v_lshl_add_u64 v[76:77], s[34:35], 0, v[76:77]
	v_cvt_pk_bf16_f32 v73, v78, v79
	v_cvt_pk_bf16_f32 v74, v80, v81
	v_cvt_pk_bf16_f32 v75, v82, v83
	v_lshl_add_u64 v[76:77], v[76:77], 0, v[120:121]
	global_store_dwordx4 v[76:77], v[72:75], off
	s_nop 1
	v_lshlrev_b32_e32 v72, 16, v128
	v_and_b32_e32 v73, 0xffff0000, v128
	v_pk_mul_f32 v[68:69], v[68:69], v[72:73]
	v_lshlrev_b32_e32 v72, 16, v129
	v_and_b32_e32 v73, 0xffff0000, v129
	v_pk_mul_f32 v[70:71], v[70:71], v[72:73]
	v_lshlrev_b32_e32 v72, 16, v130
	v_and_b32_e32 v73, 0xffff0000, v130
	v_pk_mul_f32 v[72:73], v[64:65], v[72:73]
	v_lshlrev_b32_e32 v64, 16, v131
	v_and_b32_e32 v65, 0xffff0000, v131
	v_pk_mul_f32 v[74:75], v[66:67], v[64:65]
	v_cvt_pk_bf16_f32 v64, v68, v69
	v_cvt_pk_bf16_f32 v65, v70, v71
	v_cvt_pk_bf16_f32 v66, v72, v73
	v_cvt_pk_bf16_f32 v67, v74, v75
	global_store_dwordx4 v[76:77], v[64:67], off offset:256
	v_add_u32_e32 v96, 0x80, v134
	s_nop 0
	v_mad_i64_i32 v[64:65], s[4:5], v96, s81, v[132:133]
	v_add_u32_e32 v98, 0x90, v134
	global_load_dwordx4 v[68:71], v[64:65], off
	global_load_dwordx4 v[72:75], v[64:65], off offset:256
	v_mad_i64_i32 v[64:65], s[4:5], v98, s81, v[132:133]
	v_add_u32_e32 v100, 0xa0, v134
	global_load_dwordx4 v[76:79], v[64:65], off
	global_load_dwordx4 v[80:83], v[64:65], off offset:256
	v_mad_i64_i32 v[64:65], s[4:5], v100, s81, v[132:133]
	v_add_u32_e32 v102, 0xb0, v134
	global_load_dwordx4 v[84:87], v[64:65], off
	global_load_dwordx4 v[88:91], v[64:65], off offset:256
	v_mad_i64_i32 v[64:65], s[4:5], v102, s81, v[132:133]
	global_load_dwordx4 v[92:95], v[64:65], off
	s_nop 0
	global_load_dwordx4 v[64:67], v[64:65], off offset:256
	v_ashrrev_i32_e32 v97, 31, v96
	v_ashrrev_i32_e32 v99, 31, v98
	v_ashrrev_i32_e32 v101, 31, v100
	v_ashrrev_i32_e32 v103, 31, v102
	s_waitcnt vmcnt(7)
	v_lshlrev_b32_e32 v104, 16, v68
	v_and_b32_e32 v105, 0xffff0000, v68
	v_lshlrev_b32_e32 v68, 16, v69
	v_and_b32_e32 v69, 0xffff0000, v69
	v_pk_mul_f32 v[62:63], v[62:63], v[68:69]
	v_lshlrev_b32_e32 v68, 16, v70
	v_and_b32_e32 v69, 0xffff0000, v70
	v_pk_mul_f32 v[60:61], v[60:61], v[104:105]
	v_pk_mul_f32 v[68:69], v[56:57], v[68:69]
	v_lshlrev_b32_e32 v56, 16, v71
	v_and_b32_e32 v57, 0xffff0000, v71
	v_pk_mul_f32 v[70:71], v[58:59], v[56:57]
	v_cvt_pk_bf16_f32 v56, v60, v61
	v_lshlrev_b64 v[60:61], 11, v[96:97]
	v_lshl_add_u64 v[60:61], s[34:35], 0, v[60:61]
	v_cvt_pk_bf16_f32 v57, v62, v63
	v_cvt_pk_bf16_f32 v58, v68, v69
	v_cvt_pk_bf16_f32 v59, v70, v71
	v_lshl_add_u64 v[60:61], v[60:61], 0, v[120:121]
	global_store_dwordx4 v[60:61], v[56:59], off
	s_waitcnt vmcnt(7)
	s_nop 0
	v_lshlrev_b32_e32 v56, 16, v72
	v_and_b32_e32 v57, 0xffff0000, v72
	v_pk_mul_f32 v[52:53], v[52:53], v[56:57]
	v_lshlrev_b32_e32 v56, 16, v73
	v_and_b32_e32 v57, 0xffff0000, v73
	v_pk_mul_f32 v[54:55], v[54:55], v[56:57]
	v_lshlrev_b32_e32 v56, 16, v74
	v_and_b32_e32 v57, 0xffff0000, v74
	v_pk_mul_f32 v[56:57], v[44:45], v[56:57]
	v_lshlrev_b32_e32 v44, 16, v75
	v_and_b32_e32 v45, 0xffff0000, v75
	v_pk_mul_f32 v[58:59], v[46:47], v[44:45]
	v_cvt_pk_bf16_f32 v44, v52, v53
	v_cvt_pk_bf16_f32 v45, v54, v55
	v_cvt_pk_bf16_f32 v46, v56, v57
	v_cvt_pk_bf16_f32 v47, v58, v59
	global_store_dwordx4 v[60:61], v[44:47], off offset:256
	s_waitcnt vmcnt(7)
	s_nop 0
	v_lshlrev_b32_e32 v44, 16, v76
	v_and_b32_e32 v45, 0xffff0000, v76
	v_pk_mul_f32 v[44:45], v[48:49], v[44:45]
	v_lshlrev_b32_e32 v48, 16, v78
	v_and_b32_e32 v49, 0xffff0000, v78
	v_lshlrev_b32_e32 v46, 16, v77
	v_and_b32_e32 v47, 0xffff0000, v77
	v_pk_mul_f32 v[48:49], v[40:41], v[48:49]
	v_lshlrev_b32_e32 v40, 16, v79
	v_and_b32_e32 v41, 0xffff0000, v79
	v_pk_mul_f32 v[46:47], v[50:51], v[46:47]
	v_pk_mul_f32 v[50:51], v[42:43], v[40:41]
	v_cvt_pk_bf16_f32 v40, v44, v45
	v_lshlrev_b64 v[44:45], 11, v[98:99]
	v_lshl_add_u64 v[44:45], s[34:35], 0, v[44:45]
	v_cvt_pk_bf16_f32 v41, v46, v47
	v_cvt_pk_bf16_f32 v42, v48, v49
	v_cvt_pk_bf16_f32 v43, v50, v51
	v_lshl_add_u64 v[44:45], v[44:45], 0, v[120:121]
	global_store_dwordx4 v[44:45], v[40:43], off
	s_waitcnt vmcnt(7)
	s_nop 0
	v_lshlrev_b32_e32 v40, 16, v80
	v_and_b32_e32 v41, 0xffff0000, v80
	v_pk_mul_f32 v[36:37], v[36:37], v[40:41]
	v_lshlrev_b32_e32 v40, 16, v81
	v_and_b32_e32 v41, 0xffff0000, v81
	v_pk_mul_f32 v[38:39], v[38:39], v[40:41]
	v_lshlrev_b32_e32 v40, 16, v82
	v_and_b32_e32 v41, 0xffff0000, v82
	v_pk_mul_f32 v[40:41], v[28:29], v[40:41]
	v_lshlrev_b32_e32 v28, 16, v83
	v_and_b32_e32 v29, 0xffff0000, v83
	v_pk_mul_f32 v[42:43], v[30:31], v[28:29]
	v_cvt_pk_bf16_f32 v28, v36, v37
	v_cvt_pk_bf16_f32 v29, v38, v39
	v_cvt_pk_bf16_f32 v30, v40, v41
	v_cvt_pk_bf16_f32 v31, v42, v43
	global_store_dwordx4 v[44:45], v[28:31], off offset:256
	s_waitcnt vmcnt(7)
	s_nop 0
	v_lshlrev_b32_e32 v28, 16, v84
	v_and_b32_e32 v29, 0xffff0000, v84
	v_pk_mul_f32 v[28:29], v[32:33], v[28:29]
	v_lshlrev_b32_e32 v32, 16, v86
	v_and_b32_e32 v33, 0xffff0000, v86
	v_lshlrev_b32_e32 v30, 16, v85
	v_and_b32_e32 v31, 0xffff0000, v85
	v_pk_mul_f32 v[32:33], v[24:25], v[32:33]
	v_lshlrev_b32_e32 v24, 16, v87
	v_and_b32_e32 v25, 0xffff0000, v87
	v_pk_mul_f32 v[30:31], v[34:35], v[30:31]
	v_pk_mul_f32 v[34:35], v[26:27], v[24:25]
	v_cvt_pk_bf16_f32 v24, v28, v29
	v_lshlrev_b64 v[28:29], 11, v[100:101]
	v_lshl_add_u64 v[28:29], s[34:35], 0, v[28:29]
	v_cvt_pk_bf16_f32 v25, v30, v31
	v_cvt_pk_bf16_f32 v26, v32, v33
	v_cvt_pk_bf16_f32 v27, v34, v35
	v_lshl_add_u64 v[28:29], v[28:29], 0, v[120:121]
	global_store_dwordx4 v[28:29], v[24:27], off
	s_waitcnt vmcnt(7)
	s_nop 0
	v_lshlrev_b32_e32 v24, 16, v88
	v_and_b32_e32 v25, 0xffff0000, v88
	v_pk_mul_f32 v[20:21], v[20:21], v[24:25]
	v_lshlrev_b32_e32 v24, 16, v89
	v_and_b32_e32 v25, 0xffff0000, v89
	v_pk_mul_f32 v[22:23], v[22:23], v[24:25]
	v_lshlrev_b32_e32 v24, 16, v90
	v_and_b32_e32 v25, 0xffff0000, v90
	v_pk_mul_f32 v[24:25], v[12:13], v[24:25]
	v_lshlrev_b32_e32 v12, 16, v91
	v_and_b32_e32 v13, 0xffff0000, v91
	v_pk_mul_f32 v[26:27], v[14:15], v[12:13]
	v_cvt_pk_bf16_f32 v12, v20, v21
	v_cvt_pk_bf16_f32 v13, v22, v23
	v_cvt_pk_bf16_f32 v14, v24, v25
	v_cvt_pk_bf16_f32 v15, v26, v27
	global_store_dwordx4 v[28:29], v[12:15], off offset:256
	s_waitcnt vmcnt(7)
	s_nop 0
	v_lshlrev_b32_e32 v12, 16, v92
	v_and_b32_e32 v13, 0xffff0000, v92
	v_pk_mul_f32 v[12:13], v[16:17], v[12:13]
	v_lshlrev_b32_e32 v16, 16, v94
	v_and_b32_e32 v17, 0xffff0000, v94
	v_lshlrev_b32_e32 v14, 16, v93
	v_and_b32_e32 v15, 0xffff0000, v93
	v_pk_mul_f32 v[16:17], v[8:9], v[16:17]
	v_lshlrev_b32_e32 v8, 16, v95
	v_and_b32_e32 v9, 0xffff0000, v95
	v_pk_mul_f32 v[14:15], v[18:19], v[14:15]
	v_pk_mul_f32 v[18:19], v[10:11], v[8:9]
	v_cvt_pk_bf16_f32 v8, v12, v13
	v_lshlrev_b64 v[12:13], 11, v[102:103]
	v_lshl_add_u64 v[12:13], s[34:35], 0, v[12:13]
	v_cvt_pk_bf16_f32 v9, v14, v15
	v_cvt_pk_bf16_f32 v10, v16, v17
	v_cvt_pk_bf16_f32 v11, v18, v19
	v_lshl_add_u64 v[12:13], v[12:13], 0, v[120:121]
	global_store_dwordx4 v[12:13], v[8:11], off
	s_waitcnt vmcnt(7)
	s_nop 0
	v_lshlrev_b32_e32 v8, 16, v64
	v_and_b32_e32 v9, 0xffff0000, v64
	v_pk_mul_f32 v[4:5], v[4:5], v[8:9]
	v_lshlrev_b32_e32 v8, 16, v65
	v_and_b32_e32 v9, 0xffff0000, v65
	v_pk_mul_f32 v[6:7], v[6:7], v[8:9]
	v_lshlrev_b32_e32 v8, 16, v66
	v_and_b32_e32 v9, 0xffff0000, v66
	v_pk_mul_f32 v[8:9], v[0:1], v[8:9]
	v_lshlrev_b32_e32 v0, 16, v67
	v_and_b32_e32 v1, 0xffff0000, v67
	v_pk_mul_f32 v[10:11], v[2:3], v[0:1]
	v_cvt_pk_bf16_f32 v0, v4, v5
	v_cvt_pk_bf16_f32 v1, v6, v7
	v_cvt_pk_bf16_f32 v2, v8, v9
	v_cvt_pk_bf16_f32 v3, v10, v11
	global_store_dwordx4 v[12:13], v[0:3], off offset:256
	s_and_b64 vcc, exec, s[0:1]
	s_mov_b64 s[0:1], -1
	s_cbranch_vccnz .LBB0_602
	s_andn2_b64 vcc, exec, s[10:11]
	s_cbranch_vccnz .LBB0_601
	s_barrier
	s_branch .LBB0_601
